# v31 + P0 XN loop: ln1 gain vectors loaded once before the loop (were re-loaded after every store group with vmcnt(0) = store-ack + L2 round trip, 3x per trip); vmcnt/s_nop re-derived
# baseline (speedup 1.0000x reference)
.LBB0_60:
	s_or_b64 exec, exec, s[2:3]
	s_add_i32 s0, s0, 32
	s_and_b32 s0, s0, 0x7ff
	s_cmpk_gt_i32 s0, 0x101f
	s_cbranch_scc1 .LBB0_63
	s_lshl_b32 s0, s0, 2
	v_mov_b32_e32 v71, 0
	s_lshl_b32 s1, s71, 5
	v_lshl_add_u64 v[74:75], s[90:91], 0, v[70:71]
	s_ashr_i32 s16, s0, 31
	s_ashr_i32 s17, s1, 31
	v_lshlrev_b32_e32 v70, 4, v190
	s_movk_i32 s20, 0x1000
	s_movk_i32 s21, 0x2000
	s_movk_i32 s22, 0x3000
	v_mov_b32_e32 v80, 0x358637bd
	s_mov_b32 s23, 0xf800000
	v_mov_b32_e32 v81, 0x260
	v_lshlrev_b32_e32 v76, 3, v190
	v_mov_b32_e32 v77, v71
	s_movk_i32 s24, 0x7fff
	s_mov_b32 s25, 0xffff0000
	global_load_dwordx4 v[110:113], v[74:75], off
	global_load_dwordx4 v[114:117], v[74:75], off offset:1024
	global_load_dwordx4 v[118:121], v[74:75], off offset:2048
	global_load_dwordx4 v[122:125], v[74:75], off offset:3072
.LBB0_62:
	s_add_i32 s2, s0, 0xffffc000
	s_cmpk_gt_i32 s0, 0x3fff
	s_cselect_b32 s3, 0, s16
	s_cselect_b32 s2, s2, s0
	s_cselect_b32 s8, s79, s77
	s_cselect_b32 s9, s78, s76
	s_cselect_b32 s6, s29, s97
	s_cselect_b32 s7, s28, s96
	s_lshl_b64 s[4:5], s[2:3], 12
	s_add_u32 s4, s9, s4
	s_addc_u32 s5, s8, s5
	v_lshl_add_u64 v[10:11], s[4:5], 0, v[70:71]
	v_add_co_u32_e32 v12, vcc, s20, v10
	global_load_dwordx4 v[66:69], v70, s[4:5] nt
	global_load_dwordx4 v[62:65], v70, s[4:5] offset:1024 nt
	global_load_dwordx4 v[54:57], v70, s[4:5] offset:2048 nt
	global_load_dwordx4 v[6:9], v70, s[4:5] offset:3072 nt
	v_addc_co_u32_e32 v13, vcc, 0, v11, vcc
	v_add_co_u32_e32 v14, vcc, s21, v10
	s_lshl_b64 s[2:3], s[2:3], 11
	s_nop 0
	v_addc_co_u32_e32 v15, vcc, 0, v11, vcc
	v_add_co_u32_e32 v18, vcc, s22, v10
	s_add_u32 s14, s7, s2
	s_nop 0
	v_addc_co_u32_e32 v19, vcc, 0, v11, vcc
	global_load_dwordx4 v[58:61], v[14:15], off offset:-4096 nt
	global_load_dwordx4 v[50:53], v[12:13], off offset:1024 nt
	global_load_dwordx4 v[46:49], v[12:13], off offset:2048 nt
	s_nop 0
	global_load_dwordx4 v[10:13], v[12:13], off offset:3072 nt
	s_nop 0
	global_load_dwordx4 v[42:45], v[14:15], off nt
	global_load_dwordx4 v[38:41], v[14:15], off offset:1024 nt
	global_load_dwordx4 v[34:37], v[14:15], off offset:2048 nt
	s_nop 0
	global_load_dwordx4 v[14:17], v[14:15], off offset:3072 nt
	s_nop 0
	global_load_dwordx4 v[30:33], v[18:19], off nt
	global_load_dwordx4 v[26:29], v[18:19], off offset:1024 nt
	global_load_dwordx4 v[22:25], v[18:19], off offset:2048 nt
	s_nop 0
	global_load_dwordx4 v[18:21], v[18:19], off offset:3072 nt
	s_addc_u32 s15, s6, s3
	v_lshl_add_u64 v[78:79], s[14:15], 0, v[76:77]
	v_add_co_u32_e32 v78, vcc, s20, v78
	s_add_u32 s0, s0, s1
	s_nop 0
	v_addc_co_u32_e32 v79, vcc, 0, v79, vcc
	s_addc_u32 s16, s16, s17
	s_cmpk_gt_i32 s0, 0x407f
	s_waitcnt vmcnt(15)
	v_mul_f32_e32 v82, v67, v67
	v_mul_f32_e32 v83, v69, v69
	s_waitcnt vmcnt(14)
	v_mul_f32_e32 v84, v63, v63
	v_mul_f32_e32 v85, v65, v65
	s_waitcnt vmcnt(13)
	v_mul_f32_e32 v86, v55, v55
	v_mul_f32_e32 v87, v57, v57
	s_waitcnt vmcnt(12)
	v_mul_f32_e32 v88, v7, v7
	v_mul_f32_e32 v89, v9, v9
	v_fmac_f32_e32 v82, v66, v66
	v_fmac_f32_e32 v83, v68, v68
	v_fmac_f32_e32 v84, v62, v62
	v_fmac_f32_e32 v85, v64, v64
	v_fmac_f32_e32 v86, v54, v54
	v_fmac_f32_e32 v87, v56, v56
	v_fmac_f32_e32 v88, v6, v6
	v_fmac_f32_e32 v89, v8, v8
	v_add_f32_e32 v82, v82, v83
	v_add_f32_e32 v83, v84, v85
	v_add_f32_e32 v84, v86, v87
	v_add_f32_e32 v85, v88, v89
	s_waitcnt vmcnt(11)
	v_mul_f32_e32 v86, v59, v59
	v_mul_f32_e32 v87, v61, v61
	s_waitcnt vmcnt(10)
	v_mul_f32_e32 v88, v51, v51
	v_mul_f32_e32 v89, v53, v53
	v_add_f32_e32 v82, v82, v83
	s_waitcnt vmcnt(9)
	v_mul_f32_e32 v90, v47, v47
	v_mul_f32_e32 v91, v49, v49
	s_waitcnt vmcnt(8)
	v_mul_f32_e32 v92, v11, v11
	v_mul_f32_e32 v93, v13, v13
	s_waitcnt vmcnt(7)
	v_mul_f32_e32 v94, v43, v43
	v_mul_f32_e32 v95, v45, v45
	s_waitcnt vmcnt(6)
	v_mul_f32_e32 v96, v39, v39
	v_mul_f32_e32 v97, v41, v41
	s_waitcnt vmcnt(3)
	v_mul_f32_e32 v102, v31, v31
	v_mul_f32_e32 v103, v33, v33
	s_waitcnt vmcnt(2)
	v_mul_f32_e32 v104, v27, v27
	v_mul_f32_e32 v105, v29, v29
	v_fmac_f32_e32 v86, v58, v58
	v_fmac_f32_e32 v87, v60, v60
	v_fmac_f32_e32 v88, v50, v50
	v_fmac_f32_e32 v89, v52, v52
	v_add_f32_e32 v82, v82, v84
	v_mul_f32_e32 v98, v35, v35
	v_mul_f32_e32 v99, v37, v37
	s_waitcnt vmcnt(1)
	v_mul_f32_e32 v106, v23, v23
	v_mul_f32_e32 v107, v25, v25
	v_fmac_f32_e32 v90, v46, v46
	v_fmac_f32_e32 v91, v48, v48
	v_fmac_f32_e32 v92, v10, v10
	v_fmac_f32_e32 v93, v12, v12
	v_fmac_f32_e32 v94, v42, v42
	v_fmac_f32_e32 v95, v44, v44
	v_fmac_f32_e32 v96, v38, v38
	v_fmac_f32_e32 v97, v40, v40
	v_fmac_f32_e32 v102, v30, v30
	v_fmac_f32_e32 v103, v32, v32
	v_fmac_f32_e32 v104, v26, v26
	v_fmac_f32_e32 v105, v28, v28
	v_add_f32_e32 v83, v86, v87
	v_add_f32_e32 v84, v88, v89
	v_add_f32_e32 v82, v82, v85
	v_mul_f32_e32 v100, v15, v15
	v_mul_f32_e32 v101, v17, v17
	s_waitcnt vmcnt(0)
	v_mul_f32_e32 v108, v19, v19
	v_mul_f32_e32 v109, v21, v21
	v_fmac_f32_e32 v98, v34, v34
	v_fmac_f32_e32 v99, v36, v36
	v_fmac_f32_e32 v106, v22, v22
	v_fmac_f32_e32 v107, v24, v24
	v_add_f32_e32 v86, v90, v91
	v_add_f32_e32 v87, v92, v93
	v_add_f32_e32 v88, v94, v95
	v_add_f32_e32 v89, v96, v97
	v_add_f32_e32 v92, v102, v103
	v_add_f32_e32 v93, v104, v105
	v_add_f32_e32 v83, v83, v84
	v_add_f32_dpp v82, v82, v82 quad_perm:[1,0,3,2] row_mask:0xf bank_mask:0xf bound_ctrl:1
	v_fmac_f32_e32 v100, v14, v14
	v_fmac_f32_e32 v101, v16, v16
	v_fmac_f32_e32 v108, v18, v18
	v_fmac_f32_e32 v109, v20, v20
	v_add_f32_e32 v90, v98, v99
	v_add_f32_e32 v94, v106, v107
	v_add_f32_e32 v84, v88, v89
	v_add_f32_e32 v85, v92, v93
	v_add_f32_e32 v83, v83, v86
	v_add_f32_dpp v82, v82, v82 quad_perm:[2,3,0,1] row_mask:0xf bank_mask:0xf bound_ctrl:1
	v_add_f32_e32 v91, v100, v101
	v_add_f32_e32 v95, v108, v109
	v_add_f32_e32 v84, v84, v90
	v_add_f32_e32 v85, v85, v94
	v_add_f32_e32 v83, v83, v87
	v_add_f32_dpp v82, v82, v82 row_half_mirror row_mask:0xf bank_mask:0xf bound_ctrl:1
	v_add_f32_e32 v84, v84, v91
	v_add_f32_e32 v85, v85, v95
	v_add_f32_dpp v83, v83, v83 quad_perm:[1,0,3,2] row_mask:0xf bank_mask:0xf bound_ctrl:1
	v_add_f32_dpp v82, v82, v82 row_mirror row_mask:0xf bank_mask:0xf bound_ctrl:1
	v_add_f32_dpp v84, v84, v84 quad_perm:[1,0,3,2] row_mask:0xf bank_mask:0xf bound_ctrl:1
	v_add_f32_dpp v85, v85, v85 quad_perm:[1,0,3,2] row_mask:0xf bank_mask:0xf bound_ctrl:1
	v_add_f32_dpp v83, v83, v83 quad_perm:[2,3,0,1] row_mask:0xf bank_mask:0xf bound_ctrl:1
	v_mov_b32_e32 v86, v82
	v_add_f32_dpp v84, v84, v84 quad_perm:[2,3,0,1] row_mask:0xf bank_mask:0xf bound_ctrl:1
	v_add_f32_dpp v85, v85, v85 quad_perm:[2,3,0,1] row_mask:0xf bank_mask:0xf bound_ctrl:1
	v_add_f32_dpp v83, v83, v83 row_half_mirror row_mask:0xf bank_mask:0xf bound_ctrl:1
	v_permlane16_swap_b32_e32 v82, v86
	v_add_f32_dpp v84, v84, v84 row_half_mirror row_mask:0xf bank_mask:0xf bound_ctrl:1
	v_add_f32_dpp v85, v85, v85 row_half_mirror row_mask:0xf bank_mask:0xf bound_ctrl:1
	v_add_f32_dpp v83, v83, v83 row_mirror row_mask:0xf bank_mask:0xf bound_ctrl:1
	v_add_f32_e32 v82, v82, v86
	v_add_f32_dpp v84, v84, v84 row_mirror row_mask:0xf bank_mask:0xf bound_ctrl:1
	v_add_f32_dpp v85, v85, v85 row_mirror row_mask:0xf bank_mask:0xf bound_ctrl:1
	v_mov_b32_e32 v86, v83
	v_mov_b32_e32 v89, v82
	v_mov_b32_e32 v87, v84
	v_mov_b32_e32 v88, v85
	v_permlane16_swap_b32_e32 v83, v86
	v_permlane32_swap_b32_e32 v82, v89
	v_permlane16_swap_b32_e32 v84, v87
	v_permlane16_swap_b32_e32 v85, v88
	v_add_f32_e32 v83, v83, v86
	v_add_f32_e32 v82, v82, v89
	v_add_f32_e32 v84, v84, v87
	v_add_f32_e32 v85, v85, v88
	v_mov_b32_e32 v86, v83
	v_fmamk_f32 v82, v82, 0x3a800000, v80
	v_mov_b32_e32 v87, v84
	v_mov_b32_e32 v88, v85
	v_permlane32_swap_b32_e32 v83, v86
	v_mul_f32_e32 v89, 0x4f800000, v82
	v_cmp_gt_f32_e32 vcc, s23, v82
	v_permlane32_swap_b32_e32 v84, v87
	v_permlane32_swap_b32_e32 v85, v88
	v_add_f32_e32 v83, v83, v86
	v_cndmask_b32_e32 v82, v82, v89, vcc
	v_add_f32_e32 v84, v84, v87
	v_add_f32_e32 v85, v85, v88
	v_fmamk_f32 v83, v83, 0x3a800000, v80
	v_sqrt_f32_e32 v86, v82
	v_fmamk_f32 v84, v84, 0x3a800000, v80
	v_fmamk_f32 v85, v85, 0x3a800000, v80
	v_mul_f32_e32 v87, 0x4f800000, v83
	v_cmp_gt_f32_e64 s[6:7], s23, v83
	v_mul_f32_e32 v88, 0x4f800000, v84
	v_cmp_gt_f32_e64 s[2:3], s23, v84
	v_mul_f32_e32 v89, 0x4f800000, v85
	v_cmp_gt_f32_e64 s[4:5], s23, v85
	v_cndmask_b32_e64 v83, v83, v87, s[6:7]
	v_cndmask_b32_e64 v84, v84, v88, s[2:3]
	v_cndmask_b32_e64 v85, v85, v89, s[4:5]
	v_sqrt_f32_e32 v87, v83
	v_sqrt_f32_e32 v88, v84
	v_sqrt_f32_e32 v89, v85
	v_add_u32_e32 v90, -1, v86
	v_add_u32_e32 v91, 1, v86
	v_fma_f32 v92, -v90, v86, v82
	v_fma_f32 v93, -v91, v86, v82
	v_cmp_ge_f32_e64 s[8:9], 0, v92
	v_add_u32_e32 v92, 1, v87
	v_add_u32_e32 v94, -1, v88
	v_cndmask_b32_e64 v86, v86, v90, s[8:9]
	v_add_u32_e32 v90, -1, v87
	v_cmp_lt_f32_e64 s[8:9], 0, v93
	v_add_u32_e32 v96, -1, v89
	v_add_u32_e32 v95, 1, v88
	v_cndmask_b32_e64 v86, v86, v91, s[8:9]
	v_fma_f32 v91, -v90, v87, v83
	v_add_u32_e32 v97, 1, v89
	v_fma_f32 v93, -v92, v87, v83
	v_fma_f32 v98, -v94, v88, v84
	v_fma_f32 v100, -v96, v89, v85
	v_cmp_ge_f32_e64 s[8:9], 0, v91
	v_fma_f32 v99, -v95, v88, v84
	v_fma_f32 v101, -v97, v89, v85
	v_cndmask_b32_e64 v87, v87, v90, s[8:9]
	v_cmp_lt_f32_e64 s[8:9], 0, v93
	v_mul_f32_e32 v90, 0x37800000, v86
	v_cmp_ge_f32_e64 s[10:11], 0, v98
	v_cmp_ge_f32_e64 s[12:13], 0, v100
	v_cndmask_b32_e32 v86, v86, v90, vcc
	v_cndmask_b32_e64 v88, v88, v94, s[10:11]
	v_cmp_lt_f32_e64 s[10:11], 0, v99
	v_cndmask_b32_e64 v89, v89, v96, s[12:13]
	v_cmp_lt_f32_e64 s[12:13], 0, v101
	v_cndmask_b32_e64 v87, v87, v92, s[8:9]
	v_cmp_class_f32_e32 vcc, v82, v81
	v_cndmask_b32_e64 v88, v88, v95, s[10:11]
	v_cndmask_b32_e64 v89, v89, v97, s[12:13]
	v_cndmask_b32_e32 v82, v86, v82, vcc
	v_mul_f32_e32 v86, 0x37800000, v87
	v_mul_f32_e32 v90, 0x37800000, v88
	v_mul_f32_e32 v91, 0x37800000, v89
	v_div_scale_f32 v92, s[8:9], v82, v82, 1.0
	v_cndmask_b32_e64 v86, v87, v86, s[6:7]
	v_cmp_class_f32_e64 s[6:7], v83, v81
	v_cndmask_b32_e64 v87, v88, v90, s[2:3]
	v_cmp_class_f32_e64 s[2:3], v84, v81
	v_cndmask_b32_e64 v88, v89, v91, s[4:5]
	v_rcp_f32_e32 v89, v92
	v_cndmask_b32_e64 v83, v86, v83, s[6:7]
	v_cmp_class_f32_e64 s[4:5], v85, v81
	v_cndmask_b32_e64 v84, v87, v84, s[2:3]
	v_div_scale_f32 v86, s[2:3], v83, v83, 1.0
	v_cndmask_b32_e64 v85, v88, v85, s[4:5]
	v_div_scale_f32 v88, s[4:5], v84, v84, 1.0
	v_rcp_f32_e32 v95, v86
	v_div_scale_f32 v91, s[6:7], v85, v85, 1.0
	v_rcp_f32_e32 v96, v88
	v_rcp_f32_e32 v97, v91
	v_fma_f32 v98, -v92, v89, 1.0
	v_div_scale_f32 v93, vcc, 1.0, v82, 1.0
	v_fmac_f32_e32 v89, v98, v89
	v_mul_f32_e32 v98, v93, v89
	v_fma_f32 v99, -v86, v95, 1.0
	v_div_scale_f32 v87, s[2:3], 1.0, v83, 1.0
	v_fma_f32 v100, -v88, v96, 1.0
	v_fma_f32 v102, -v92, v98, v93
	v_fmac_f32_e32 v95, v99, v95
	v_div_scale_f32 v90, s[4:5], 1.0, v84, 1.0
	v_fma_f32 v101, -v91, v97, 1.0
	v_fmac_f32_e32 v96, v100, v96
	v_fmac_f32_e32 v98, v102, v89
	v_mul_f32_e32 v99, v87, v95
	v_div_scale_f32 v94, s[6:7], 1.0, v85, 1.0
	v_fmac_f32_e32 v97, v101, v97
	v_mul_f32_e32 v100, v90, v96
	v_fma_f32 v92, -v92, v98, v93
	v_fma_f32 v93, -v86, v99, v87
	v_mul_f32_e32 v101, v94, v97
	v_fma_f32 v102, -v88, v100, v90
	v_div_fmas_f32 v89, v92, v89, v98
	v_fmac_f32_e32 v99, v93, v95
	v_fma_f32 v103, -v91, v101, v94
	v_fmac_f32_e32 v100, v102, v96
	v_div_fixup_f32 v82, v89, v82, 1.0
	v_fma_f32 v86, -v86, v99, v87
	s_mov_b64 vcc, s[2:3]
	v_fmac_f32_e32 v101, v103, v97
	v_fma_f32 v87, -v88, v100, v90
	v_div_fmas_f32 v86, v86, v95, v99
	v_mul_f32_e32 v66, v82, v66
	v_mul_f32_e32 v68, v82, v68
	s_mov_b64 vcc, s[4:5]
	v_fma_f32 v88, -v91, v101, v94
	v_mul_f32_e32 v67, v82, v67
	v_mul_f32_e32 v69, v82, v69
	v_div_fixup_f32 v83, v86, v83, 1.0
	v_div_fmas_f32 v86, v87, v96, v100
	v_mul_f32_e32 v66, v110, v66
	v_mul_f32_e32 v68, v112, v68
	s_mov_b64 vcc, s[6:7]
	v_mul_f32_e32 v67, v111, v67
	v_mul_f32_e32 v69, v113, v69
	v_mul_f32_e32 v58, v83, v58
	v_mul_f32_e32 v60, v83, v60
	v_div_fixup_f32 v84, v86, v84, 1.0
	v_div_fmas_f32 v86, v88, v97, v101
	v_bfe_u32 v87, v66, 16, 1
	v_bfe_u32 v89, v68, 16, 1
	v_mul_f32_e32 v59, v83, v59
	v_mul_f32_e32 v61, v83, v61
	v_bfe_u32 v88, v67, 16, 1
	v_bfe_u32 v90, v69, 16, 1
	v_mul_f32_e32 v42, v84, v42
	v_mul_f32_e32 v44, v84, v44
	v_div_fixup_f32 v85, v86, v85, 1.0
	v_mul_f32_e32 v58, v110, v58
	v_mul_f32_e32 v60, v112, v60
	v_add3_u32 v66, v66, v87, s24
	v_add3_u32 v68, v68, v89, s24
	v_mul_f32_e32 v43, v84, v43
	v_mul_f32_e32 v45, v84, v45
	v_mul_f32_e32 v59, v111, v59
	v_mul_f32_e32 v61, v113, v61
	v_add3_u32 v67, v67, v88, s24
	v_add3_u32 v69, v69, v90, s24
	v_mul_f32_e32 v30, v85, v30
	v_mul_f32_e32 v31, v85, v31
	v_mul_f32_e32 v32, v85, v32
	v_mul_f32_e32 v42, v110, v42
	v_mul_f32_e32 v44, v112, v44
	v_mul_f32_e32 v86, v85, v22
	v_mul_f32_e32 v87, v85, v23
	v_mul_f32_e32 v88, v85, v24
	v_lshrrev_b32_e32 v22, 16, v66
	v_lshrrev_b32_e32 v23, 16, v68
	v_bfe_u32 v24, v58, 16, 1
	v_bfe_u32 v66, v60, 16, 1
	v_mul_f32_e32 v33, v85, v33
	v_mul_f32_e32 v43, v111, v43
	v_mul_f32_e32 v45, v113, v45
	v_mul_f32_e32 v89, v85, v25
	v_bfe_u32 v25, v59, 16, 1
	v_bfe_u32 v68, v61, 16, 1
	v_mul_f32_e32 v30, v110, v30
	v_mul_f32_e32 v31, v111, v31
	v_mul_f32_e32 v4, v112, v32
	v_and_or_b32 v2, v67, s25, v22
	v_and_or_b32 v3, v69, s25, v23
	v_add3_u32 v22, v58, v24, s24
	v_add3_u32 v24, v60, v66, s24
	v_bfe_u32 v32, v42, 16, 1
	v_bfe_u32 v58, v44, 16, 1
	v_mul_f32_e32 v5, v113, v33
	v_add3_u32 v23, v59, v25, s24
	v_add3_u32 v25, v61, v68, s24
	v_bfe_u32 v33, v43, 16, 1
	v_bfe_u32 v59, v45, 16, 1
	global_store_dwordx2 v76, v[2:3], s[14:15]
	v_lshrrev_b32_e32 v2, 16, v22
	v_lshrrev_b32_e32 v3, 16, v24
	v_add3_u32 v22, v42, v32, s24
	v_add3_u32 v32, v44, v58, s24
	v_bfe_u32 v42, v30, 16, 1
	v_bfe_u32 v44, v4, 16, 1
	v_add3_u32 v24, v43, v33, s24
	v_add3_u32 v33, v45, v59, s24
	v_bfe_u32 v43, v31, 16, 1
	v_bfe_u32 v45, v5, 16, 1
	v_and_or_b32 v2, v23, s25, v2
	v_and_or_b32 v3, v25, s25, v3
	v_lshrrev_b32_e32 v22, 16, v22
	v_lshrrev_b32_e32 v23, 16, v32
	v_add3_u32 v25, v30, v42, s24
	v_add3_u32 v4, v4, v44, s24
	v_add3_u32 v30, v31, v43, s24
	v_add3_u32 v5, v5, v45, s24
	global_store_dwordx2 v76, v[2:3], s[14:15] offset:2048
	v_and_or_b32 v2, v24, s25, v22
	v_and_or_b32 v3, v33, s25, v23
	v_lshrrev_b32_e32 v22, 16, v25
	v_lshrrev_b32_e32 v4, 16, v4
	global_store_dwordx2 v[78:79], v[2:3], off
	v_and_or_b32 v2, v30, s25, v22
	v_and_or_b32 v3, v5, s25, v4
	global_store_dwordx2 v[78:79], v[2:3], off offset:2048
	v_mul_f32_e32 v62, v82, v62
	v_mul_f32_e32 v64, v82, v64
	v_mul_f32_e32 v63, v82, v63
	v_mul_f32_e32 v65, v82, v65
	v_mul_f32_e32 v50, v83, v50
	v_mul_f32_e32 v51, v83, v51
	v_mul_f32_e32 v52, v83, v52
	v_mul_f32_e32 v53, v83, v53
	v_mul_f32_e32 v38, v84, v38
	v_mul_f32_e32 v39, v84, v39
	v_mul_f32_e32 v40, v84, v40
	v_mul_f32_e32 v41, v84, v41
	v_mul_f32_e32 v26, v85, v26
	v_mul_f32_e32 v27, v85, v27
	v_mul_f32_e32 v28, v85, v28
	v_mul_f32_e32 v29, v85, v29
	v_mul_f32_e32 v54, v82, v54
	v_mul_f32_e32 v56, v82, v56
	v_mul_f32_e32 v55, v82, v55
	v_mul_f32_e32 v57, v82, v57
	v_mul_f32_e32 v46, v83, v46
	v_mul_f32_e32 v47, v83, v47
	v_mul_f32_e32 v48, v83, v48
	v_mul_f32_e32 v49, v83, v49
	v_mul_f32_e32 v34, v84, v34
	v_mul_f32_e32 v35, v84, v35
	v_mul_f32_e32 v36, v84, v36
	v_mul_f32_e32 v37, v84, v37
	v_mul_f32_e32 v6, v82, v6
	v_mul_f32_e32 v8, v82, v8
	v_mul_f32_e32 v7, v82, v7
	v_mul_f32_e32 v9, v82, v9
	v_mul_f32_e32 v10, v83, v10
	v_mul_f32_e32 v11, v83, v11
	v_mul_f32_e32 v12, v83, v12
	v_mul_f32_e32 v13, v83, v13
	v_mul_f32_e32 v14, v84, v14
	v_mul_f32_e32 v15, v84, v15
	v_mul_f32_e32 v16, v84, v16
	v_mul_f32_e32 v17, v84, v17
	v_mul_f32_e32 v18, v85, v18
	v_mul_f32_e32 v19, v85, v19
	v_mul_f32_e32 v20, v85, v20
	v_mul_f32_e32 v21, v85, v21
	v_mul_f32_e32 v22, v114, v62
	v_mul_f32_e32 v24, v116, v64
	v_mul_f32_e32 v23, v115, v63
	v_mul_f32_e32 v25, v117, v65
	v_mul_f32_e32 v30, v114, v50
	v_mul_f32_e32 v31, v115, v51
	v_mul_f32_e32 v32, v116, v52
	v_mul_f32_e32 v33, v117, v53
	v_mul_f32_e32 v38, v114, v38
	v_mul_f32_e32 v39, v115, v39
	v_mul_f32_e32 v40, v116, v40
	v_mul_f32_e32 v41, v117, v41
	v_mul_f32_e32 v2, v114, v26
	v_mul_f32_e32 v3, v115, v27
	v_mul_f32_e32 v4, v116, v28
	v_mul_f32_e32 v5, v117, v29
	v_bfe_u32 v26, v22, 16, 1
	v_bfe_u32 v28, v24, 16, 1
	v_bfe_u32 v27, v23, 16, 1
	v_bfe_u32 v29, v25, 16, 1
	v_bfe_u32 v42, v30, 16, 1
	v_bfe_u32 v43, v31, 16, 1
	v_bfe_u32 v44, v32, 16, 1
	v_bfe_u32 v50, v38, 16, 1
	v_bfe_u32 v51, v39, 16, 1
	v_bfe_u32 v52, v40, 16, 1
	v_bfe_u32 v58, v2, 16, 1
	v_bfe_u32 v59, v3, 16, 1
	v_bfe_u32 v60, v4, 16, 1
	v_bfe_u32 v61, v5, 16, 1
	v_add3_u32 v22, v22, v26, s24
	v_add3_u32 v24, v24, v28, s24
	v_bfe_u32 v45, v33, 16, 1
	v_bfe_u32 v53, v41, 16, 1
	v_add3_u32 v23, v23, v27, s24
	v_add3_u32 v25, v25, v29, s24
	v_add3_u32 v26, v30, v42, s24
	v_add3_u32 v27, v31, v43, s24
	v_add3_u32 v28, v32, v44, s24
	v_add3_u32 v30, v38, v50, s24
	v_add3_u32 v31, v39, v51, s24
	v_add3_u32 v32, v40, v52, s24
	v_add3_u32 v2, v2, v58, s24
	v_add3_u32 v38, v3, v59, s24
	v_add3_u32 v3, v4, v60, s24
	v_add3_u32 v39, v5, v61, s24
	v_lshrrev_b32_e32 v4, 16, v22
	v_lshrrev_b32_e32 v5, 16, v24
	v_add3_u32 v29, v33, v45, s24
	v_add3_u32 v33, v41, v53, s24
	v_lshrrev_b32_e32 v22, 16, v26
	v_lshrrev_b32_e32 v24, 16, v28
	v_lshrrev_b32_e32 v26, 16, v30
	v_lshrrev_b32_e32 v28, 16, v32
	v_lshrrev_b32_e32 v30, 16, v2
	v_lshrrev_b32_e32 v32, 16, v3
	v_and_or_b32 v2, v23, s25, v4
	v_and_or_b32 v3, v25, s25, v5
	v_and_or_b32 v4, v27, s25, v22
	v_and_or_b32 v5, v29, s25, v24
	v_and_or_b32 v22, v31, s25, v26
	v_and_or_b32 v23, v33, s25, v28
	v_and_or_b32 v24, v38, s25, v30
	v_and_or_b32 v25, v39, s25, v32
	global_store_dwordx2 v76, v[2:3], s[14:15] offset:512
	global_store_dwordx2 v76, v[4:5], s[14:15] offset:2560
	global_store_dwordx2 v[78:79], v[22:23], off offset:512
	global_store_dwordx2 v[78:79], v[24:25], off offset:2560
	v_mul_f32_e32 v22, v118, v54
	v_mul_f32_e32 v24, v120, v56
	v_mul_f32_e32 v23, v119, v55
	v_mul_f32_e32 v25, v121, v57
	v_mul_f32_e32 v26, v118, v46
	v_mul_f32_e32 v27, v119, v47
	v_mul_f32_e32 v28, v120, v48
	v_mul_f32_e32 v29, v121, v49
	v_mul_f32_e32 v30, v118, v34
	v_mul_f32_e32 v31, v119, v35
	v_mul_f32_e32 v32, v120, v36
	v_mul_f32_e32 v33, v121, v37
	v_mul_f32_e32 v2, v118, v86
	v_mul_f32_e32 v3, v119, v87
	v_mul_f32_e32 v4, v120, v88
	v_mul_f32_e32 v5, v121, v89
	v_bfe_u32 v34, v22, 16, 1
	v_bfe_u32 v36, v24, 16, 1
	v_bfe_u32 v35, v23, 16, 1
	v_bfe_u32 v37, v25, 16, 1
	v_bfe_u32 v38, v26, 16, 1
	v_bfe_u32 v40, v28, 16, 1
	v_bfe_u32 v42, v30, 16, 1
	v_bfe_u32 v44, v32, 16, 1
	v_bfe_u32 v46, v2, 16, 1
	v_bfe_u32 v47, v3, 16, 1
	v_bfe_u32 v48, v4, 16, 1
	v_bfe_u32 v49, v5, 16, 1
	v_add3_u32 v22, v22, v34, s24
	v_add3_u32 v24, v24, v36, s24
	v_bfe_u32 v39, v27, 16, 1
	v_bfe_u32 v41, v29, 16, 1
	v_bfe_u32 v43, v31, 16, 1
	v_bfe_u32 v45, v33, 16, 1
	v_add3_u32 v23, v23, v35, s24
	v_add3_u32 v25, v25, v37, s24
	v_add3_u32 v26, v26, v38, s24
	v_add3_u32 v28, v28, v40, s24
	v_add3_u32 v30, v30, v42, s24
	v_add3_u32 v32, v32, v44, s24
	v_add3_u32 v2, v2, v46, s24
	v_add3_u32 v34, v3, v47, s24
	v_add3_u32 v3, v4, v48, s24
	v_add3_u32 v35, v5, v49, s24
	v_lshrrev_b32_e32 v4, 16, v22
	v_lshrrev_b32_e32 v5, 16, v24
	v_add3_u32 v27, v27, v39, s24
	v_add3_u32 v29, v29, v41, s24
	v_add3_u32 v31, v31, v43, s24
	v_add3_u32 v33, v33, v45, s24
	v_lshrrev_b32_e32 v22, 16, v26
	v_lshrrev_b32_e32 v24, 16, v28
	v_lshrrev_b32_e32 v26, 16, v30
	v_lshrrev_b32_e32 v28, 16, v32
	v_lshrrev_b32_e32 v30, 16, v2
	v_lshrrev_b32_e32 v32, 16, v3
	v_and_or_b32 v2, v23, s25, v4
	v_and_or_b32 v3, v25, s25, v5
	v_and_or_b32 v4, v27, s25, v22
	v_and_or_b32 v5, v29, s25, v24
	v_and_or_b32 v22, v31, s25, v26
	v_and_or_b32 v23, v33, s25, v28
	v_and_or_b32 v24, v34, s25, v30
	v_and_or_b32 v25, v35, s25, v32
	global_store_dwordx2 v76, v[2:3], s[14:15] offset:1024
	global_store_dwordx2 v76, v[4:5], s[14:15] offset:3072
	global_store_dwordx2 v[78:79], v[22:23], off offset:1024
	global_store_dwordx2 v[78:79], v[24:25], off offset:3072
	v_mul_f32_e32 v6, v122, v6
	v_mul_f32_e32 v8, v124, v8
	v_mul_f32_e32 v7, v123, v7
	v_mul_f32_e32 v9, v125, v9
	v_mul_f32_e32 v10, v122, v10
	v_mul_f32_e32 v11, v123, v11
	v_mul_f32_e32 v12, v124, v12
	v_mul_f32_e32 v13, v125, v13
	v_mul_f32_e32 v14, v122, v14
	v_mul_f32_e32 v15, v123, v15
	v_mul_f32_e32 v16, v124, v16
	v_mul_f32_e32 v17, v125, v17
	v_mul_f32_e32 v2, v122, v18
	v_mul_f32_e32 v3, v123, v19
	v_mul_f32_e32 v4, v124, v20
	v_mul_f32_e32 v5, v125, v21
	v_bfe_u32 v18, v6, 16, 1
	v_bfe_u32 v20, v8, 16, 1
	v_bfe_u32 v19, v7, 16, 1
	v_bfe_u32 v21, v9, 16, 1
	v_bfe_u32 v22, v10, 16, 1
	v_bfe_u32 v24, v12, 16, 1
	v_bfe_u32 v26, v14, 16, 1
	v_bfe_u32 v28, v16, 16, 1
	v_bfe_u32 v30, v2, 16, 1
	v_bfe_u32 v31, v3, 16, 1
	v_bfe_u32 v32, v4, 16, 1
	v_bfe_u32 v33, v5, 16, 1
	v_add3_u32 v6, v6, v18, s24
	v_add3_u32 v8, v8, v20, s24
	v_bfe_u32 v23, v11, 16, 1
	v_bfe_u32 v25, v13, 16, 1
	v_bfe_u32 v27, v15, 16, 1
	v_bfe_u32 v29, v17, 16, 1
	v_add3_u32 v7, v7, v19, s24
	v_add3_u32 v9, v9, v21, s24
	v_add3_u32 v10, v10, v22, s24
	v_add3_u32 v12, v12, v24, s24
	v_add3_u32 v14, v14, v26, s24
	v_add3_u32 v16, v16, v28, s24
	v_add3_u32 v2, v2, v30, s24
	v_add3_u32 v18, v3, v31, s24
	v_add3_u32 v3, v4, v32, s24
	v_add3_u32 v19, v5, v33, s24
	v_lshrrev_b32_e32 v4, 16, v6
	v_lshrrev_b32_e32 v5, 16, v8
	v_add3_u32 v11, v11, v23, s24
	v_add3_u32 v13, v13, v25, s24
	v_add3_u32 v15, v15, v27, s24
	v_add3_u32 v17, v17, v29, s24
	v_lshrrev_b32_e32 v6, 16, v10
	v_lshrrev_b32_e32 v8, 16, v12
	v_lshrrev_b32_e32 v10, 16, v14
	v_lshrrev_b32_e32 v12, 16, v16
	v_lshrrev_b32_e32 v14, 16, v2
	v_lshrrev_b32_e32 v16, 16, v3
	v_and_or_b32 v2, v7, s25, v4
	v_and_or_b32 v3, v9, s25, v5
	v_and_or_b32 v4, v11, s25, v6
	v_and_or_b32 v5, v13, s25, v8
	v_and_or_b32 v6, v15, s25, v10
	v_and_or_b32 v7, v17, s25, v12
	v_and_or_b32 v8, v18, s25, v14
	v_and_or_b32 v9, v19, s25, v16
	global_store_dwordx2 v76, v[2:3], s[14:15] offset:1536
	global_store_dwordx2 v76, v[4:5], s[14:15] offset:3584
	global_store_dwordx2 v[78:79], v[6:7], off offset:1536
	global_store_dwordx2 v[78:79], v[8:9], off offset:3584
	s_cbranch_scc0 .LBB0_62
